# v55 + P0 conditioning-vector fill (silu(c) into LDS): ten independent loads issued together instead of ten serial kernarg-load + global-load round trips
# speedup vs baseline: 1.0102x; 1.0102x over previous
.LBB0_1752:
	s_and_b64 vcc, exec, s[8:9]
	s_cbranch_vccz .LBB0_1924
	s_mov_b64 s[8:9], s[0:1]
	v_mov_b32_e32 v69, v202
	s_load_dwordx2 s[26:27], s[8:9], 0x38
	s_load_dwordx2 s[16:17], s[8:9], 0x30
	s_mov_b64 s[4:5], exec
	v_readfirstlane_b32 s83, v69
	v_lshlrev_b32_e32 v4, 2, v69
	v_add_u32_e32 v5, 0x1000, v4
	v_add_u32_e32 v6, 0x2000, v4
	v_add_u32_e32 v7, 0x3000, v4
	s_waitcnt lgkmcnt(0)
	global_load_dword v10, v4, s[26:27]
	global_load_dword v11, v4, s[26:27] offset:2048
	global_load_dword v12, v4, s[16:17]
	global_load_dword v13, v4, s[16:17] offset:2048
	global_load_dword v14, v5, s[16:17]
	global_load_dword v15, v5, s[16:17] offset:2048
	global_load_dword v16, v6, s[16:17]
	global_load_dword v17, v6, s[16:17] offset:2048
	global_load_dword v18, v7, s[16:17]
	global_load_dword v19, v7, s[16:17] offset:2048
	s_waitcnt vmcnt(9)
	v_max_f32_e32 v2, v10, v10
	v_max_f32_e32 v2, 0xc1f00000, v2
	v_min_f32_e32 v2, 0x41f00000, v2
	v_mul_f32_e32 v2, 0xbfb8aa3b, v2
	v_exp_f32_e32 v2, v2
	s_nop 0
	v_add_f32_e32 v2, 1.0, v2
	v_rcp_f32_e32 v2, v2
	s_nop 0
	v_mul_f32_e32 v10, v10, v2
	ds_write_b32 v4, v10 offset:0
	s_waitcnt vmcnt(8)
	v_max_f32_e32 v2, v11, v11
	v_max_f32_e32 v2, 0xc1f00000, v2
	v_min_f32_e32 v2, 0x41f00000, v2
	v_mul_f32_e32 v2, 0xbfb8aa3b, v2
	v_exp_f32_e32 v2, v2
	s_nop 0
	v_add_f32_e32 v2, 1.0, v2
	v_rcp_f32_e32 v2, v2
	s_nop 0
	v_mul_f32_e32 v11, v11, v2
	ds_write_b32 v4, v11 offset:2048
	s_waitcnt vmcnt(7)
	v_max_f32_e32 v2, v12, v12
	v_max_f32_e32 v2, 0xc1f00000, v2
	v_min_f32_e32 v2, 0x41f00000, v2
	v_mul_f32_e32 v2, 0xbfb8aa3b, v2
	v_exp_f32_e32 v2, v2
	s_nop 0
	v_add_f32_e32 v2, 1.0, v2
	v_rcp_f32_e32 v2, v2
	s_nop 0
	v_mul_f32_e32 v12, v12, v2
	ds_write_b32 v4, v12 offset:4096
	s_waitcnt vmcnt(6)
	v_max_f32_e32 v2, v13, v13
	v_max_f32_e32 v2, 0xc1f00000, v2
	v_min_f32_e32 v2, 0x41f00000, v2
	v_mul_f32_e32 v2, 0xbfb8aa3b, v2
	v_exp_f32_e32 v2, v2
	s_nop 0
	v_add_f32_e32 v2, 1.0, v2
	v_rcp_f32_e32 v2, v2
	s_nop 0
	v_mul_f32_e32 v13, v13, v2
	ds_write_b32 v4, v13 offset:6144
	s_waitcnt vmcnt(5)
	v_max_f32_e32 v2, v14, v14
	v_max_f32_e32 v2, 0xc1f00000, v2
	v_min_f32_e32 v2, 0x41f00000, v2
	v_mul_f32_e32 v2, 0xbfb8aa3b, v2
	v_exp_f32_e32 v2, v2
	s_nop 0
	v_add_f32_e32 v2, 1.0, v2
	v_rcp_f32_e32 v2, v2
	s_nop 0
	v_mul_f32_e32 v14, v14, v2
	ds_write_b32 v4, v14 offset:8192
	s_waitcnt vmcnt(4)
	v_max_f32_e32 v2, v15, v15
	v_max_f32_e32 v2, 0xc1f00000, v2
	v_min_f32_e32 v2, 0x41f00000, v2
	v_mul_f32_e32 v2, 0xbfb8aa3b, v2
	v_exp_f32_e32 v2, v2
	s_nop 0
	v_add_f32_e32 v2, 1.0, v2
	v_rcp_f32_e32 v2, v2
	s_nop 0
	v_mul_f32_e32 v15, v15, v2
	ds_write_b32 v4, v15 offset:10240
	s_waitcnt vmcnt(3)
	v_max_f32_e32 v2, v16, v16
	v_max_f32_e32 v2, 0xc1f00000, v2
	v_min_f32_e32 v2, 0x41f00000, v2
	v_mul_f32_e32 v2, 0xbfb8aa3b, v2
	v_exp_f32_e32 v2, v2
	s_nop 0
	v_add_f32_e32 v2, 1.0, v2
	v_rcp_f32_e32 v2, v2
	s_nop 0
	v_mul_f32_e32 v16, v16, v2
	ds_write_b32 v4, v16 offset:12288
	s_waitcnt vmcnt(2)
	v_max_f32_e32 v2, v17, v17
	v_max_f32_e32 v2, 0xc1f00000, v2
	v_min_f32_e32 v2, 0x41f00000, v2
	v_mul_f32_e32 v2, 0xbfb8aa3b, v2
	v_exp_f32_e32 v2, v2
	s_nop 0
	v_add_f32_e32 v2, 1.0, v2
	v_rcp_f32_e32 v2, v2
	s_nop 0
	v_mul_f32_e32 v17, v17, v2
	ds_write_b32 v4, v17 offset:14336
	s_waitcnt vmcnt(1)
	v_max_f32_e32 v2, v18, v18
	v_max_f32_e32 v2, 0xc1f00000, v2
	v_min_f32_e32 v2, 0x41f00000, v2
	v_mul_f32_e32 v2, 0xbfb8aa3b, v2
	v_exp_f32_e32 v2, v2
	s_nop 0
	v_add_f32_e32 v2, 1.0, v2
	v_rcp_f32_e32 v2, v2
	s_nop 0
	v_mul_f32_e32 v18, v18, v2
	ds_write_b32 v4, v18 offset:16384
	s_waitcnt vmcnt(0)
	v_max_f32_e32 v2, v19, v19
	v_max_f32_e32 v2, 0xc1f00000, v2
	v_min_f32_e32 v2, 0x41f00000, v2
	v_mul_f32_e32 v2, 0xbfb8aa3b, v2
	v_exp_f32_e32 v2, v2
	s_nop 0
	v_add_f32_e32 v2, 1.0, v2
	v_rcp_f32_e32 v2, v2
	s_nop 0
	v_mul_f32_e32 v19, v19, v2
	ds_write_b32 v4, v19 offset:18432
